# v35 + slab-line prefetch at the top of each 5-row batch in the three norm row passes
# baseline (speedup 1.0000x reference)
.LBB0_620:
	v_lshrrev_b32_e32 v210, 5, v204
	v_lshlrev_b32_e32 v211, 4, v204
	v_and_b32_e32 v211, 0x1f0, v211
	v_add_u32_e32 v211, 0x4d00000, v211
	s_mov_b32 s99, 0x60000
	s_add_i32 s98, s12, 0
	s_lshr_b32 s2, s98, 8
	s_lshl_b32 s2, s2, 2
	v_add_u32_e32 v212, s2, v210
	ds_read_u8 v217, v212
	ds_read_u8 v222, v212 offset:2
	s_add_i32 s98, s12, 1
	s_lshr_b32 s2, s98, 8
	s_lshl_b32 s2, s2, 2
	v_add_u32_e32 v213, s2, v210
	ds_read_u8 v218, v213
	ds_read_u8 v223, v213 offset:2
	s_add_i32 s98, s12, 2
	s_lshr_b32 s2, s98, 8
	s_lshl_b32 s2, s2, 2
	v_add_u32_e32 v214, s2, v210
	ds_read_u8 v219, v214
	ds_read_u8 v224, v214 offset:2
	s_add_i32 s98, s12, 3
	s_lshr_b32 s2, s98, 8
	s_lshl_b32 s2, s2, 2
	v_add_u32_e32 v215, s2, v210
	ds_read_u8 v220, v215
	ds_read_u8 v225, v215 offset:2
	s_add_i32 s98, s12, 4
	s_lshr_b32 s2, s98, 8
	s_lshl_b32 s2, s2, 2
	v_add_u32_e32 v216, s2, v210
	ds_read_u8 v221, v216
	ds_read_u8 v226, v216 offset:2
	s_waitcnt lgkmcnt(0)
	v_min_u32_e32 v217, v217, v222
	s_add_i32 s98, s12, 0
	s_and_b32 s98, s98, 0xff
	s_lshl_b32 s98, s98, 9
	v_add_u32_e32 v212, s98, v211
	v_mad_u32_u24 v212, v217, s99, v212
	v_cmp_ne_u32_e32 vcc, 0xff, v217
	s_and_saveexec_b64 s[100:101], vcc
	s_cbranch_execz .Lspf_0_0
	global_load_dwordx4 v[228:231], v212, s[56:57]
	v_add_u32_e32 v222, 0x20000, v212
	global_load_dwordx4 v[232:235], v222, s[56:57]
	v_add_u32_e32 v222, 0x40000, v212
	global_load_dwordx4 v[236:239], v222, s[56:57]
.Lspf_0_0:
	s_mov_b64 exec, s[100:101]
	v_min_u32_e32 v218, v218, v223
	s_add_i32 s98, s12, 1
	s_and_b32 s98, s98, 0xff
	s_lshl_b32 s98, s98, 9
	v_add_u32_e32 v213, s98, v211
	v_mad_u32_u24 v213, v218, s99, v213
	v_cmp_ne_u32_e32 vcc, 0xff, v218
	s_and_saveexec_b64 s[100:101], vcc
	s_cbranch_execz .Lspf_0_1
	global_load_dwordx4 v[228:231], v213, s[56:57]
	v_add_u32_e32 v223, 0x20000, v213
	global_load_dwordx4 v[232:235], v223, s[56:57]
	v_add_u32_e32 v223, 0x40000, v213
	global_load_dwordx4 v[236:239], v223, s[56:57]
.Lspf_0_1:
	s_mov_b64 exec, s[100:101]
	v_min_u32_e32 v219, v219, v224
	s_add_i32 s98, s12, 2
	s_and_b32 s98, s98, 0xff
	s_lshl_b32 s98, s98, 9
	v_add_u32_e32 v214, s98, v211
	v_mad_u32_u24 v214, v219, s99, v214
	v_cmp_ne_u32_e32 vcc, 0xff, v219
	s_and_saveexec_b64 s[100:101], vcc
	s_cbranch_execz .Lspf_0_2
	global_load_dwordx4 v[228:231], v214, s[56:57]
	v_add_u32_e32 v224, 0x20000, v214
	global_load_dwordx4 v[232:235], v224, s[56:57]
	v_add_u32_e32 v224, 0x40000, v214
	global_load_dwordx4 v[236:239], v224, s[56:57]
.Lspf_0_2:
	s_mov_b64 exec, s[100:101]
	v_min_u32_e32 v220, v220, v225
	s_add_i32 s98, s12, 3
	s_and_b32 s98, s98, 0xff
	s_lshl_b32 s98, s98, 9
	v_add_u32_e32 v215, s98, v211
	v_mad_u32_u24 v215, v220, s99, v215
	v_cmp_ne_u32_e32 vcc, 0xff, v220
	s_and_saveexec_b64 s[100:101], vcc
	s_cbranch_execz .Lspf_0_3
	global_load_dwordx4 v[228:231], v215, s[56:57]
	v_add_u32_e32 v225, 0x20000, v215
	global_load_dwordx4 v[232:235], v225, s[56:57]
	v_add_u32_e32 v225, 0x40000, v215
	global_load_dwordx4 v[236:239], v225, s[56:57]
.Lspf_0_3:
	s_mov_b64 exec, s[100:101]
	v_min_u32_e32 v221, v221, v226
	s_add_i32 s98, s12, 4
	s_and_b32 s98, s98, 0xff
	s_lshl_b32 s98, s98, 9
	v_add_u32_e32 v216, s98, v211
	v_mad_u32_u24 v216, v221, s99, v216
	v_cmp_ne_u32_e32 vcc, 0xff, v221
	s_and_saveexec_b64 s[100:101], vcc
	s_cbranch_execz .Lspf_0_4
	global_load_dwordx4 v[228:231], v216, s[56:57]
	v_add_u32_e32 v226, 0x20000, v216
	global_load_dwordx4 v[232:235], v226, s[56:57]
	v_add_u32_e32 v226, 0x40000, v216
	global_load_dwordx4 v[236:239], v226, s[56:57]
.Lspf_0_4:
	s_mov_b64 exec, s[100:101]
	s_ashr_i32 s2, s12, 12
	s_cmp_eq_u32 s2, s73
	s_cbranch_scc1 .LBB0_622
	s_mul_i32 s4, s2, 12
	s_ashr_i32 s5, s4, 31
	s_lshl_b64 s[4:5], s[4:5], 12
	v_lshl_add_u64 v[86:87], v[118:119], 0, s[4:5]
	v_add_co_u32_e32 v74, vcc, 0x1000, v86
	v_lshl_add_u64 v[76:77], v[86:87], 0, s[22:23]
	s_nop 0
	v_addc_co_u32_e32 v75, vcc, 0, v87, vcc
	global_load_dwordx4 v[90:93], v[74:75], off
	global_load_dwordx4 v[94:97], v[76:77], off offset:16
	global_load_dwordx4 v[98:101], v[74:75], off offset:2048
	v_lshl_add_u64 v[74:75], v[86:87], 0, s[26:27]
	global_load_dwordx4 v[102:105], v[74:75], off offset:16
	s_nop 0
	global_load_dwordx4 v[74:77], v[86:87], off offset:16
	global_load_dwordx4 v[78:81], v[86:87], off
	global_load_dwordx4 v[82:85], v[86:87], off offset:2064
	s_nop 0
	global_load_dwordx4 v[86:89], v[86:87], off offset:2048
	s_mov_b32 s73, s2
	s_waitcnt vmcnt(4)
	v_pk_add_f32 v[104:105], v[104:105], 1.0 op_sel_hi:[1,0]
	v_pk_add_f32 v[92:93], v[92:93], 1.0 op_sel_hi:[1,0]
	v_pk_add_f32 v[90:91], v[90:91], 1.0 op_sel_hi:[1,0]
	v_pk_add_f32 v[96:97], v[96:97], 1.0 op_sel_hi:[1,0]
	v_pk_add_f32 v[94:95], v[94:95], 1.0 op_sel_hi:[1,0]
	v_pk_add_f32 v[100:101], v[100:101], 1.0 op_sel_hi:[1,0]
	v_pk_add_f32 v[98:99], v[98:99], 1.0 op_sel_hi:[1,0]
	v_pk_add_f32 v[102:103], v[102:103], 1.0 op_sel_hi:[1,0]
	v_pk_mul_f32 v[92:93], v[8:9], v[92:93]
	v_pk_mul_f32 v[90:91], v[6:7], v[90:91]
	v_pk_mul_f32 v[96:97], v[4:5], v[96:97]
	v_pk_mul_f32 v[94:95], v[2:3], v[94:95]
	v_pk_mul_f32 v[100:101], v[16:17], v[100:101]
	v_pk_mul_f32 v[98:99], v[14:15], v[98:99]
	v_pk_mul_f32 v[104:105], v[12:13], v[104:105]
	v_pk_mul_f32 v[102:103], v[10:11], v[102:103]

.LBB0_888:
	v_lshrrev_b32_e32 v210, 5, v204
	v_lshlrev_b32_e32 v211, 4, v204
	v_and_b32_e32 v211, 0x1f0, v211
	v_add_u32_e32 v211, 0x3500000, v211
	s_mov_b32 s99, 0x60000
	s_add_i32 s98, s12, 0
	s_lshr_b32 s2, s98, 8
	s_lshl_b32 s2, s2, 2
	v_add_u32_e32 v212, s2, v210
	ds_read_u8 v217, v212
	ds_read_u8 v222, v212 offset:2
	s_add_i32 s98, s12, 1
	s_lshr_b32 s2, s98, 8
	s_lshl_b32 s2, s2, 2
	v_add_u32_e32 v213, s2, v210
	ds_read_u8 v218, v213
	ds_read_u8 v223, v213 offset:2
	s_add_i32 s98, s12, 2
	s_lshr_b32 s2, s98, 8
	s_lshl_b32 s2, s2, 2
	v_add_u32_e32 v214, s2, v210
	ds_read_u8 v219, v214
	ds_read_u8 v224, v214 offset:2
	s_add_i32 s98, s12, 3
	s_lshr_b32 s2, s98, 8
	s_lshl_b32 s2, s2, 2
	v_add_u32_e32 v215, s2, v210
	ds_read_u8 v220, v215
	ds_read_u8 v225, v215 offset:2
	s_add_i32 s98, s12, 4
	s_lshr_b32 s2, s98, 8
	s_lshl_b32 s2, s2, 2
	v_add_u32_e32 v216, s2, v210
	ds_read_u8 v221, v216
	ds_read_u8 v226, v216 offset:2
	s_waitcnt lgkmcnt(0)
	v_min_u32_e32 v217, v217, v222
	s_add_i32 s98, s12, 0
	s_and_b32 s98, s98, 0xff
	s_lshl_b32 s98, s98, 9
	v_add_u32_e32 v212, s98, v211
	v_mad_u32_u24 v212, v217, s99, v212
	v_cmp_ne_u32_e32 vcc, 0xff, v217
	s_and_saveexec_b64 s[100:101], vcc
	s_cbranch_execz .Lspf_1_0
	global_load_dwordx4 v[228:231], v212, s[56:57]
	v_add_u32_e32 v222, 0x20000, v212
	global_load_dwordx4 v[232:235], v222, s[56:57]
	v_add_u32_e32 v222, 0x40000, v212
	global_load_dwordx4 v[236:239], v222, s[56:57]

.Lspf_1_4:
	s_mov_b64 exec, s[100:101]
	s_ashr_i32 s2, s12, 12
	s_cmp_eq_u32 s2, s63
	s_cbranch_scc1 .LBB0_890
	s_mul_i32 s0, s2, 12
	s_ashr_i32 s1, s0, 31
	s_lshl_b64 s[0:1], s[0:1], 12
	v_lshl_add_u64 v[78:79], v[118:119], 0, s[0:1]
	v_add_co_u32_e32 v76, vcc, 0x6000, v78
	v_lshl_add_u64 v[74:75], v[78:79], 0, s[26:27]
	s_mov_b64 s[0:1], vcc
	v_add_co_u32_e32 v80, vcc, 0x7000, v78
	global_load_dwordx4 v[90:93], v[74:75], off offset:16
	s_nop 0
	v_addc_co_u32_e32 v81, vcc, 0, v79, vcc
	v_lshl_add_u64 v[74:75], v[78:79], 0, s[36:37]
	global_load_dwordx4 v[94:97], v[80:81], off
	global_load_dwordx4 v[98:101], v[80:81], off offset:2048
	global_load_dwordx4 v[102:105], v[74:75], off offset:16
	v_addc_co_u32_e64 v77, vcc, 0, v79, s[0:1]
	v_lshl_add_u64 v[86:87], v[78:79], 0, s[22:23]
	global_load_dwordx4 v[74:77], v[76:77], off
	s_nop 0
	global_load_dwordx4 v[78:81], v[86:87], off offset:2064
	global_load_dwordx4 v[82:85], v[86:87], off offset:16
	s_nop 0
	global_load_dwordx4 v[86:89], v[86:87], off offset:2048
	s_mov_b32 s63, s2
	s_waitcnt vmcnt(7)
	v_pk_add_f32 v[92:93], v[92:93], 1.0 op_sel_hi:[1,0]
	v_pk_add_f32 v[90:91], v[90:91], 1.0 op_sel_hi:[1,0]
	v_pk_mul_f32 v[92:93], v[12:13], v[92:93]
	s_waitcnt vmcnt(6)
	v_pk_add_f32 v[96:97], v[96:97], 1.0 op_sel_hi:[1,0]
	v_pk_add_f32 v[94:95], v[94:95], 1.0 op_sel_hi:[1,0]
	s_waitcnt vmcnt(5)
	v_pk_add_f32 v[100:101], v[100:101], 1.0 op_sel_hi:[1,0]
	v_pk_add_f32 v[98:99], v[98:99], 1.0 op_sel_hi:[1,0]
	s_waitcnt vmcnt(4)
	v_pk_add_f32 v[104:105], v[104:105], 1.0 op_sel_hi:[1,0]
	v_pk_add_f32 v[102:103], v[102:103], 1.0 op_sel_hi:[1,0]
	v_pk_mul_f32 v[90:91], v[10:11], v[90:91]
	v_pk_mul_f32 v[96:97], v[4:5], v[96:97]
	v_pk_mul_f32 v[94:95], v[2:3], v[94:95]
	v_pk_mul_f32 v[100:101], v[16:17], v[100:101]
	v_pk_mul_f32 v[98:99], v[14:15], v[98:99]
	v_pk_mul_f32 v[104:105], v[8:9], v[104:105]
	v_pk_mul_f32 v[102:103], v[6:7], v[102:103]

.LBB0_1495:
	v_lshrrev_b32_e32 v210, 5, v204
	v_lshlrev_b32_e32 v211, 4, v204
	v_and_b32_e32 v211, 0x1f0, v211
	v_add_u32_e32 v211, 0x4500000, v211
	s_mov_b32 s99, 0x60000
	s_add_i32 s98, s20, 0
	s_lshr_b32 s2, s98, 8
	s_lshl_b32 s2, s2, 2
	v_add_u32_e32 v212, s2, v210
	ds_read_u8 v217, v212
	ds_read_u8 v222, v212 offset:2
	s_add_i32 s98, s20, 1
	s_lshr_b32 s2, s98, 8
	s_lshl_b32 s2, s2, 2
	v_add_u32_e32 v213, s2, v210
	ds_read_u8 v218, v213
	ds_read_u8 v223, v213 offset:2
	s_add_i32 s98, s20, 2
	s_lshr_b32 s2, s98, 8
	s_lshl_b32 s2, s2, 2
	v_add_u32_e32 v214, s2, v210
	ds_read_u8 v219, v214
	ds_read_u8 v224, v214 offset:2
	s_add_i32 s98, s20, 3
	s_lshr_b32 s2, s98, 8
	s_lshl_b32 s2, s2, 2
	v_add_u32_e32 v215, s2, v210
	ds_read_u8 v220, v215
	ds_read_u8 v225, v215 offset:2
	s_add_i32 s98, s20, 4
	s_lshr_b32 s2, s98, 8
	s_lshl_b32 s2, s2, 2
	v_add_u32_e32 v216, s2, v210
	ds_read_u8 v221, v216
	ds_read_u8 v226, v216 offset:2
	s_waitcnt lgkmcnt(0)
	v_min_u32_e32 v217, v217, v222
	s_add_i32 s98, s20, 0
	s_and_b32 s98, s98, 0xff
	s_lshl_b32 s98, s98, 9
	v_add_u32_e32 v212, s98, v211
	v_mad_u32_u24 v212, v217, s99, v212
	v_cmp_ne_u32_e32 vcc, 0xff, v217
	s_and_saveexec_b64 s[100:101], vcc
	s_cbranch_execz .Lspf_2_0
	global_load_dwordx4 v[228:231], v212, s[56:57]
	v_add_u32_e32 v222, 0x20000, v212
	global_load_dwordx4 v[232:235], v222, s[56:57]
	v_add_u32_e32 v222, 0x40000, v212
	global_load_dwordx4 v[236:239], v222, s[56:57]
.Lspf_2_0:
	s_mov_b64 exec, s[100:101]
	v_min_u32_e32 v218, v218, v223
	s_add_i32 s98, s20, 1
	s_and_b32 s98, s98, 0xff
	s_lshl_b32 s98, s98, 9
	v_add_u32_e32 v213, s98, v211
	v_mad_u32_u24 v213, v218, s99, v213
	v_cmp_ne_u32_e32 vcc, 0xff, v218
	s_and_saveexec_b64 s[100:101], vcc
	s_cbranch_execz .Lspf_2_1
	global_load_dwordx4 v[228:231], v213, s[56:57]
	v_add_u32_e32 v223, 0x20000, v213
	global_load_dwordx4 v[232:235], v223, s[56:57]
	v_add_u32_e32 v223, 0x40000, v213
	global_load_dwordx4 v[236:239], v223, s[56:57]
.Lspf_2_1:
	s_mov_b64 exec, s[100:101]
	v_min_u32_e32 v219, v219, v224
	s_add_i32 s98, s20, 2
	s_and_b32 s98, s98, 0xff
	s_lshl_b32 s98, s98, 9
	v_add_u32_e32 v214, s98, v211
	v_mad_u32_u24 v214, v219, s99, v214
	v_cmp_ne_u32_e32 vcc, 0xff, v219
	s_and_saveexec_b64 s[100:101], vcc
	s_cbranch_execz .Lspf_2_2
	global_load_dwordx4 v[228:231], v214, s[56:57]
	v_add_u32_e32 v224, 0x20000, v214
	global_load_dwordx4 v[232:235], v224, s[56:57]
	v_add_u32_e32 v224, 0x40000, v214
	global_load_dwordx4 v[236:239], v224, s[56:57]
.Lspf_2_2:
	s_mov_b64 exec, s[100:101]
	v_min_u32_e32 v220, v220, v225
	s_add_i32 s98, s20, 3
	s_and_b32 s98, s98, 0xff
	s_lshl_b32 s98, s98, 9
	v_add_u32_e32 v215, s98, v211
	v_mad_u32_u24 v215, v220, s99, v215
	v_cmp_ne_u32_e32 vcc, 0xff, v220
	s_and_saveexec_b64 s[100:101], vcc
	s_cbranch_execz .Lspf_2_3
	global_load_dwordx4 v[228:231], v215, s[56:57]
	v_add_u32_e32 v225, 0x20000, v215
	global_load_dwordx4 v[232:235], v225, s[56:57]
	v_add_u32_e32 v225, 0x40000, v215
	global_load_dwordx4 v[236:239], v225, s[56:57]
.Lspf_2_3:
	s_mov_b64 exec, s[100:101]
	v_min_u32_e32 v221, v221, v226
	s_add_i32 s98, s20, 4
	s_and_b32 s98, s98, 0xff
	s_lshl_b32 s98, s98, 9
	v_add_u32_e32 v216, s98, v211
	v_mad_u32_u24 v216, v221, s99, v216
	v_cmp_ne_u32_e32 vcc, 0xff, v221
	s_and_saveexec_b64 s[100:101], vcc
	s_cbranch_execz .Lspf_2_4
	global_load_dwordx4 v[228:231], v216, s[56:57]
	v_add_u32_e32 v226, 0x20000, v216
	global_load_dwordx4 v[232:235], v226, s[56:57]
	v_add_u32_e32 v226, 0x40000, v216
	global_load_dwordx4 v[236:239], v226, s[56:57]
.Lspf_2_4:
	s_mov_b64 exec, s[100:101]
	s_ashr_i32 s2, s20, 12
	s_cmp_eq_u32 s2, s51
	s_cbranch_scc1 .LBB0_1497
	s_mul_i32 s0, s2, 12
	s_ashr_i32 s1, s0, 31
	s_lshl_b64 s[0:1], s[0:1], 12
	v_lshl_add_u64 v[78:79], v[118:119], 0, s[0:1]
	v_add_co_u32_e32 v76, vcc, 0x6000, v78
	v_lshl_add_u64 v[74:75], v[78:79], 0, s[24:25]
	s_mov_b64 s[0:1], vcc
	v_add_co_u32_e32 v80, vcc, 0x7000, v78
	global_load_dwordx4 v[90:93], v[74:75], off offset:16
	s_nop 0
	v_addc_co_u32_e32 v81, vcc, 0, v79, vcc
	v_lshl_add_u64 v[74:75], v[78:79], 0, s[26:27]
	global_load_dwordx4 v[94:97], v[80:81], off
	global_load_dwordx4 v[98:101], v[80:81], off offset:2048
	global_load_dwordx4 v[102:105], v[74:75], off offset:16
	v_addc_co_u32_e64 v77, vcc, 0, v79, s[0:1]
	v_lshl_add_u64 v[86:87], v[78:79], 0, s[22:23]
	global_load_dwordx4 v[74:77], v[76:77], off
	s_nop 0
	global_load_dwordx4 v[78:81], v[86:87], off offset:2064
	global_load_dwordx4 v[82:85], v[86:87], off offset:16
	s_nop 0
	global_load_dwordx4 v[86:89], v[86:87], off offset:2048
	s_mov_b32 s51, s2
	s_waitcnt vmcnt(7)
	v_pk_add_f32 v[92:93], v[92:93], 1.0 op_sel_hi:[1,0]
	v_pk_add_f32 v[90:91], v[90:91], 1.0 op_sel_hi:[1,0]
	v_pk_mul_f32 v[92:93], v[12:13], v[92:93]
	s_waitcnt vmcnt(6)
	v_pk_add_f32 v[96:97], v[96:97], 1.0 op_sel_hi:[1,0]
	v_pk_add_f32 v[94:95], v[94:95], 1.0 op_sel_hi:[1,0]
	s_waitcnt vmcnt(5)
	v_pk_add_f32 v[100:101], v[100:101], 1.0 op_sel_hi:[1,0]
	v_pk_add_f32 v[98:99], v[98:99], 1.0 op_sel_hi:[1,0]
	s_waitcnt vmcnt(4)
	v_pk_add_f32 v[104:105], v[104:105], 1.0 op_sel_hi:[1,0]
	v_pk_add_f32 v[102:103], v[102:103], 1.0 op_sel_hi:[1,0]
	v_pk_mul_f32 v[90:91], v[10:11], v[90:91]
	v_pk_mul_f32 v[96:97], v[4:5], v[96:97]
	v_pk_mul_f32 v[94:95], v[2:3], v[94:95]
	v_pk_mul_f32 v[100:101], v[16:17], v[100:101]
	v_pk_mul_f32 v[98:99], v[14:15], v[98:99]
	v_pk_mul_f32 v[104:105], v[8:9], v[104:105]
	v_pk_mul_f32 v[102:103], v[6:7], v[102:103]
